# MoBA loop: one workgroup barrier per TWO tiles (after each barrier the two K and two V ring slots read before it are refilled; all pieces waited at the end of the second tile)
# speedup vs baseline: 1.0133x; 1.0090x over previous
.LBB0_1059:
.LBB0_1060:
.LBB0_1062:
.Lmb1_A:
	s_barrier
	s_and_b64 vcc, exec, s[6:7]
	s_cbranch_vccz .Lmb1_A_g1top
	s_cmp_eq_u32 s37, 0
	s_cbranch_scc1 .Lmb1_f1A
	s_mov_b32 s45, s37
	s_cmp_ge_u32 s45, s30
	s_cbranch_scc1 .Lmb1_k0A
	s_mov_b32 s45, s44
	s_and_b32 s45, s45, 0x6000
	s_add_i32 s45, s45, s74
	s_mov_b32 s99, m0
	s_mov_b32 m0, s45
	s_nop 0
	global_load_lds_dwordx4 v[114:115], off
	s_mov_b32 m0, s99

.Lmb1_f1A:
	s_add_i32 s45, s37, 1
	s_cmp_ge_u32 s45, s30
	s_cbranch_scc1 .Lmb1_k1A
	s_add_i32 s45, s44, 0x2000
	s_and_b32 s45, s45, 0x6000
	s_add_i32 s45, s45, s74
	s_mov_b32 s99, m0
	s_mov_b32 m0, s45
	s_nop 0
	global_load_lds_dwordx4 v[114:115], off
	s_mov_b32 m0, s99
.Lmb1_k1A:
	v_lshl_add_u64 v[114:115], v[114:115], 0, s[22:23]
	s_cmp_eq_u32 s37, 0
	s_cbranch_scc1 .Lmb1_f2A
	s_add_i32 s45, s37, 3
	s_cmp_ge_u32 s45, s35
	s_cbranch_scc1 .Lmb1_v0A
	s_add_i32 s45, s44, 0x6000
	s_and_b32 s45, s45, 0x6000
	s_add_i32 s45, s45, s75
	s_mov_b32 s99, m0
	s_mov_b32 m0, s45
	s_nop 0
	global_load_lds_dwordx4 v[116:117], off
	s_mov_b32 m0, s99
.Lmb1_v0A:
	v_lshl_add_u64 v[116:117], v[116:117], 0, s[22:23]
.Lmb1_f2A:
	s_add_i32 s45, s37, 4
	s_cmp_ge_u32 s45, s35
	s_cbranch_scc1 .Lmb1_v1A
	s_mov_b32 s45, s44
	s_and_b32 s45, s45, 0x6000
	s_add_i32 s45, s45, s75
	s_mov_b32 s99, m0
	s_mov_b32 m0, s45
	s_nop 0
	global_load_lds_dwordx4 v[116:117], off
	s_mov_b32 m0, s99

.Lmb1_A_g1top:
	s_add_i32 s42, s44, 0x2000
	s_add_i32 s98, s44, 0x4000
	s_and_b32 s45, s98, 0x6000
	v_add_u32_e32 v133, s45, v130
	ds_read_b128 v[154:157], v133
	ds_read_b128 v[158:161], v133 offset:512
	ds_read_b128 v[162:165], v133 offset:2048
	ds_read_b128 v[166:169], v133 offset:2560
	ds_read_b128 v[170:173], v133 offset:4096
	ds_read_b128 v[174:177], v133 offset:4608
	ds_read_b128 v[178:181], v133 offset:6144
	ds_read_b128 v[182:185], v133 offset:6656
	s_and_b32 s45, s42, 0x6000
	v_add_u32_e32 v218, s45, v132
	s_add_i32 s98, s34, 2
	s_cmp_ge_i32 s34, s31
	s_cbranch_scc1 .Lmb1_A_near
	v_mfma_f32_32x32x16_bf16 v[16:31], v[108:111], v[186:189], v[16:31]
	v_exp_f32_e32 v64, v64
	v_exp_f32_e32 v48, v48
	v_mfma_f32_32x32x16_bf16 v[16:31], v[104:107], v[190:193], v[16:31]
	v_exp_f32_e32 v65, v65
	v_exp_f32_e32 v49, v49
	v_add_f32_e32 v252, v64, v48
	v_mfma_f32_32x32x16_bf16 v[16:31], v[100:103], v[194:197], v[16:31]
	v_exp_f32_e32 v66, v66
	v_exp_f32_e32 v50, v50
	v_add_f32_e32 v253, v65, v49
	v_add_f32_e32 v252, v252, v253
	v_mfma_f32_32x32x16_bf16 v[16:31], v[96:99], v[198:201], v[16:31]
	v_exp_f32_e32 v67, v67
	v_exp_f32_e32 v51, v51
	v_add_f32_e32 v253, v66, v50
	v_add_f32_e32 v252, v252, v253
	v_mfma_f32_32x32x16_bf16 v[32:47], v[108:111], v[202:205], v[32:47]
	v_exp_f32_e32 v68, v68
	v_exp_f32_e32 v52, v52
	v_add_f32_e32 v253, v67, v51
	v_add_f32_e32 v252, v252, v253
	ds_read_b64_tr_b16 v[186:187], v218
	ds_read_b64_tr_b16 v[188:189], v218 offset:512
	v_mfma_f32_32x32x16_bf16 v[32:47], v[104:107], v[206:209], v[32:47]
	v_exp_f32_e32 v69, v69
	v_exp_f32_e32 v53, v53
	v_add_f32_e32 v253, v68, v52
	v_add_f32_e32 v252, v252, v253
	ds_read_b64_tr_b16 v[190:191], v218 offset:1024
	ds_read_b64_tr_b16 v[192:193], v218 offset:1536
	v_mfma_f32_32x32x16_bf16 v[32:47], v[100:103], v[210:213], v[32:47]
	v_exp_f32_e32 v70, v70
	v_exp_f32_e32 v54, v54
	v_add_f32_e32 v253, v69, v53
	v_add_f32_e32 v252, v252, v253
	ds_read_b64_tr_b16 v[194:195], v218 offset:2048
	ds_read_b64_tr_b16 v[196:197], v218 offset:2560
	v_mfma_f32_32x32x16_bf16 v[32:47], v[96:99], v[214:217], v[32:47]
	v_exp_f32_e32 v71, v71
	v_exp_f32_e32 v55, v55
	v_add_f32_e32 v253, v70, v54
	v_add_f32_e32 v252, v252, v253
	ds_read_b64_tr_b16 v[198:199], v218 offset:3072
	ds_read_b64_tr_b16 v[200:201], v218 offset:3584
	s_and_b64 vcc, exec, s[6:7]
	s_cbranch_vccnz .Lmb1_A_g0mid
	s_cmp_eq_u32 s37, 0
	s_cbranch_scc1 .Lmb1_f1Am
	s_mov_b32 s45, s37
	s_cmp_ge_u32 s45, s30
	s_cbranch_scc1 .Lmb1_k0Am
	s_mov_b32 s45, s44
	s_and_b32 s45, s45, 0x6000
	s_add_i32 s45, s45, s74
	s_mov_b32 s99, m0
	s_mov_b32 m0, s45
	s_nop 0
	global_load_lds_dwordx4 v[114:115], off
	s_mov_b32 m0, s99

.Lmb1_A_nocin:
	v_subrev_u32_e32 v112, 64, v112
	s_add_i32 s34, s34, 1
	s_waitcnt lgkmcnt(0)

.Lmb1_B:
	s_and_b64 vcc, exec, s[6:7]
	s_cbranch_vccz .Lmb1_B_g1top
.Lmb1_B_g1top:
	s_add_i32 s42, s44, 0x2000
	s_add_i32 s98, s44, 0x4000
	s_and_b32 s45, s98, 0x6000
	v_add_u32_e32 v133, s45, v130
	ds_read_b128 v[154:157], v133
	ds_read_b128 v[158:161], v133 offset:512
	ds_read_b128 v[162:165], v133 offset:2048
	ds_read_b128 v[166:169], v133 offset:2560
	ds_read_b128 v[170:173], v133 offset:4096
	ds_read_b128 v[174:177], v133 offset:4608
	ds_read_b128 v[178:181], v133 offset:6144
	ds_read_b128 v[182:185], v133 offset:6656
	s_and_b32 s45, s42, 0x6000
	v_add_u32_e32 v218, s45, v132
	s_add_i32 s98, s34, 2
	s_cmp_ge_i32 s34, s31
	s_cbranch_scc1 .Lmb1_B_near
	v_mfma_f32_32x32x16_bf16 v[16:31], v[108:111], v[186:189], v[16:31]
	v_exp_f32_e32 v236, v236
	v_exp_f32_e32 v134, v134
	v_mfma_f32_32x32x16_bf16 v[16:31], v[104:107], v[190:193], v[16:31]
	v_exp_f32_e32 v237, v237
	v_exp_f32_e32 v135, v135
	v_add_f32_e32 v252, v236, v134
	v_mfma_f32_32x32x16_bf16 v[16:31], v[100:103], v[194:197], v[16:31]
	v_exp_f32_e32 v238, v238
	v_exp_f32_e32 v136, v136
	v_add_f32_e32 v253, v237, v135
	v_add_f32_e32 v252, v252, v253
	v_mfma_f32_32x32x16_bf16 v[16:31], v[96:99], v[198:201], v[16:31]
	v_exp_f32_e32 v239, v239
	v_exp_f32_e32 v137, v137
	v_add_f32_e32 v253, v238, v136
	v_add_f32_e32 v252, v252, v253
	v_mfma_f32_32x32x16_bf16 v[32:47], v[108:111], v[202:205], v[32:47]
	v_exp_f32_e32 v240, v240
	v_exp_f32_e32 v138, v138
	v_add_f32_e32 v253, v239, v137
	v_add_f32_e32 v252, v252, v253
	ds_read_b64_tr_b16 v[186:187], v218
	ds_read_b64_tr_b16 v[188:189], v218 offset:512
	v_mfma_f32_32x32x16_bf16 v[32:47], v[104:107], v[206:209], v[32:47]
	v_exp_f32_e32 v241, v241
	v_exp_f32_e32 v139, v139
	v_add_f32_e32 v253, v240, v138
	v_add_f32_e32 v252, v252, v253
	ds_read_b64_tr_b16 v[190:191], v218 offset:1024
	ds_read_b64_tr_b16 v[192:193], v218 offset:1536
	v_mfma_f32_32x32x16_bf16 v[32:47], v[100:103], v[210:213], v[32:47]
	v_exp_f32_e32 v242, v242
	v_exp_f32_e32 v140, v140
	v_add_f32_e32 v253, v241, v139
	v_add_f32_e32 v252, v252, v253
	ds_read_b64_tr_b16 v[194:195], v218 offset:2048
	ds_read_b64_tr_b16 v[196:197], v218 offset:2560
	v_mfma_f32_32x32x16_bf16 v[32:47], v[96:99], v[214:217], v[32:47]
	v_exp_f32_e32 v243, v243
	v_exp_f32_e32 v141, v141
	v_add_f32_e32 v253, v242, v140
	v_add_f32_e32 v252, v252, v253
	ds_read_b64_tr_b16 v[198:199], v218 offset:3072
	ds_read_b64_tr_b16 v[200:201], v218 offset:3584
	s_and_b64 vcc, exec, s[6:7]
	s_cbranch_vccnz .Lmb1_B_g0mid
.Lmb1_B_g0mid:
	s_waitcnt lgkmcnt(8)
	v_mfma_f32_32x32x16_bf16 v[64:79], v[154:157], v[92:95], v[220:235]
	v_exp_f32_e32 v244, v244
	v_exp_f32_e32 v142, v142
	v_add_f32_e32 v253, v243, v141
	v_add_f32_e32 v252, v252, v253
	v_cvt_pk_bf16_f32 v108, v236, v237
	v_cvt_pk_bf16_f32 v100, v134, v135
	ds_read_b64_tr_b16 v[202:203], v218 offset:4096
	ds_read_b64_tr_b16 v[204:205], v218 offset:4608
	v_mfma_f32_32x32x16_bf16 v[48:63], v[158:161], v[92:95], v[220:235]
	v_exp_f32_e32 v245, v245
	v_exp_f32_e32 v143, v143
	v_add_f32_e32 v253, v244, v142
	v_add_f32_e32 v252, v252, v253
	v_cvt_pk_bf16_f32 v109, v238, v239
	v_cvt_pk_bf16_f32 v101, v136, v137
	ds_read_b64_tr_b16 v[206:207], v218 offset:5120
	ds_read_b64_tr_b16 v[208:209], v218 offset:5632
	v_mfma_f32_32x32x16_bf16 v[64:79], v[162:165], v[88:91], v[64:79]
	v_exp_f32_e32 v246, v246
	v_exp_f32_e32 v144, v144
	v_add_f32_e32 v253, v245, v143
	v_add_f32_e32 v252, v252, v253
	v_cvt_pk_bf16_f32 v110, v240, v241
	v_cvt_pk_bf16_f32 v102, v138, v139
	ds_read_b64_tr_b16 v[210:211], v218 offset:6144
	ds_read_b64_tr_b16 v[212:213], v218 offset:6656
	v_mfma_f32_32x32x16_bf16 v[48:63], v[166:169], v[88:91], v[48:63]
	v_exp_f32_e32 v247, v247
	v_exp_f32_e32 v145, v145
	v_add_f32_e32 v253, v246, v144
	v_add_f32_e32 v252, v252, v253
	v_cvt_pk_bf16_f32 v111, v242, v243
	v_cvt_pk_bf16_f32 v103, v140, v141
	ds_read_b64_tr_b16 v[214:215], v218 offset:7168
	ds_read_b64_tr_b16 v[216:217], v218 offset:7680
	v_mfma_f32_32x32x16_bf16 v[64:79], v[170:173], v[84:87], v[64:79]
	v_exp_f32_e32 v248, v248
	v_exp_f32_e32 v146, v146
	v_add_f32_e32 v253, v247, v145
	v_add_f32_e32 v252, v252, v253
	v_cvt_pk_bf16_f32 v104, v244, v245
	v_cvt_pk_bf16_f32 v96, v142, v143
	v_mfma_f32_32x32x16_bf16 v[48:63], v[174:177], v[84:87], v[48:63]
	v_exp_f32_e32 v249, v249
	v_exp_f32_e32 v147, v147
	v_add_f32_e32 v253, v248, v146
	v_add_f32_e32 v252, v252, v253
	v_cvt_pk_bf16_f32 v105, v246, v247
	v_cvt_pk_bf16_f32 v97, v144, v145
	v_mfma_f32_32x32x16_bf16 v[64:79], v[178:181], v[80:83], v[64:79]
	v_exp_f32_e32 v250, v250
	v_exp_f32_e32 v148, v148
	v_add_f32_e32 v253, v249, v147
	v_add_f32_e32 v252, v252, v253
	v_cvt_pk_bf16_f32 v106, v248, v249
	v_cvt_pk_bf16_f32 v98, v146, v147
	v_mfma_f32_32x32x16_bf16 v[48:63], v[182:185], v[80:83], v[48:63]
	v_exp_f32_e32 v251, v251
	v_exp_f32_e32 v149, v149
	v_add_f32_e32 v253, v250, v148
	v_add_f32_e32 v252, v252, v253
	v_add_f32_e32 v253, v251, v149
	v_add_f32_e32 v252, v252, v253
	v_cvt_pk_bf16_f32 v107, v250, v251
	v_cvt_pk_bf16_f32 v99, v148, v149
	v_add_f32_e32 v131, v131, v252

.Lmb1_B_nocin:
	v_subrev_u32_e32 v112, 64, v112
	s_add_i32 s34, s34, 1
	s_waitcnt vmcnt(0) lgkmcnt(0)

.Lmb1_A_near:
	s_and_b64 vcc, exec, s[6:7]
	s_cbranch_vccnz .Lmb1_A_g0near
	s_cmp_eq_u32 s37, 0
	s_cbranch_scc1 .Lmb1_f1An
	s_mov_b32 s45, s37
	s_cmp_ge_u32 s45, s30
	s_cbranch_scc1 .Lmb1_k0An
	s_mov_b32 s45, s44
	s_and_b32 s45, s45, 0x6000
	s_add_i32 s45, s45, s74
	s_mov_b32 s99, m0
	s_mov_b32 m0, s45
	s_nop 0
	global_load_lds_dwordx4 v[114:115], off
	s_mov_b32 m0, s99

.Lmb1_B_near:
	s_and_b64 vcc, exec, s[6:7]
	s_cbranch_vccnz .Lmb1_B_g0near
; #define ATT_LAS __attribute__((address_space(3)))
; #define ATT_MFMA(a, b, c) __builtin_amdgcn_mfma_f32_32x32x16_bf16((a), (b), (c), 0, 0, 0)
; __device__ __forceinline__ void qkt(f32x16& p0, f32x16& p1, lds_cptr kb, const bf16x8* qr, const f32x16& z) {
; #pragma unroll
;     for (int d0 = 0; d0 < 4; ++d0) {
;         const bf16x8 b0 = *(const ATT_LAS bf16x8*)(kb + d0 * 2048);
;         const bf16x8 b1 = *(const ATT_LAS bf16x8*)(kb + d0 * 2048 + 512);
;         if (d0 == 0) { p0 = ATT_MFMA(b0, qr[0], z); p1 = ATT_MFMA(b1, qr[0], z); }
;         else { p0 = ATT_MFMA(b0, qr[d0], p0); p1 = ATT_MFMA(b1, qr[d0], p1); } }
; }
; __device__ __forceinline__ void pv(f32x16* o, int vb, bf16x8 pa0, bf16x8 pa1, bf16x8 pa2, bf16x8 pa3) {
; #pragma unroll
;     for (int d0 = 0; d0 < 2; ++d0) { s16x4 lo[4], hi[4];
; #pragma unroll
;         for (int ks = 0; ks < 4; ++ks) {
;             asm volatile("ds_read_b64_tr_b16 %0,%1 offset:%c2" : "=&v"(lo[ks]) : "v"(vb), "i"(d0 * 4096 + ks * 1024) : "memory");
;             asm volatile("ds_read_b64_tr_b16 %0,%1 offset:%c2" : "=&v"(hi[ks]) : "v"(vb), "i"(d0 * 4096 + ks * 1024 + 512) : "memory"); }
;         asm volatile("s_waitcnt lgkmcnt(0)" ::: "memory"); __builtin_amdgcn_sched_barrier(0);
;     ...
;         o[d0] = ATT_MFMA(pa0, ATT_PK(0), o[d0]);
;         o[d0] = ATT_MFMA(pa1, ATT_PK(1), o[d0]);
;         o[d0] = ATT_MFMA(pa2, ATT_PK(2), o[d0]);
;         o[d0] = ATT_MFMA(pa3, ATT_PK(3), o[d0]);
;     ...
;     }
; }
.Lmb1_B_g0near:
	s_waitcnt lgkmcnt(8)
	v_mfma_f32_32x32x16_bf16 v[16:31], v[108:111], v[186:189], v[16:31]
	v_mfma_f32_32x32x16_bf16 v[16:31], v[104:107], v[190:193], v[16:31]
	v_mfma_f32_32x32x16_bf16 v[16:31], v[100:103], v[194:197], v[16:31]
	v_mfma_f32_32x32x16_bf16 v[16:31], v[96:99], v[198:201], v[16:31]
	v_mfma_f32_32x32x16_bf16 v[32:47], v[108:111], v[202:205], v[32:47]
	v_mfma_f32_32x32x16_bf16 v[32:47], v[104:107], v[206:209], v[32:47]
	v_mfma_f32_32x32x16_bf16 v[32:47], v[100:103], v[210:213], v[32:47]
	v_mfma_f32_32x32x16_bf16 v[32:47], v[96:99], v[214:217], v[32:47]
	s_lshr_b32 s44, s34, 2
	s_cmp_eq_u32 s44, s91
	s_cselect_b64 s[8:9], -1, 0
	s_lshl_b32 s44, 1, s44
	v_and_b32_e32 v96, s44, v129
	v_cmp_ne_u32_e32 vcc, 0, v96
	s_or_b64 vcc, s[8:9], vcc
	s_nop 0
	v_cndmask_b32_e32 v96, v127, v112, vcc
	v_lshl_add_u32 v96, v96, 2, 0
	v_add_u32_e32 v104, 0x1d000, v96
	ds_read2_b32 v[96:97], v104 offset0:58 offset1:59
	ds_read2_b32 v[98:99], v104 offset0:26 offset1:27
	ds_read2_b32 v[100:101], v104 offset0:56 offset1:57
	s_waitcnt lgkmcnt(2)
	v_pk_add_f32 v[236:237], v[236:237], v[96:97] op_sel:[0,1] op_sel_hi:[1,0]
	ds_read2_b32 v[96:97], v104 offset0:24 offset1:25
	s_waitcnt lgkmcnt(2)
	v_pk_add_f32 v[134:135], v[134:135], v[98:99] op_sel:[0,1] op_sel_hi:[1,0]
	ds_read2_b32 v[98:99], v104 offset0:50 offset1:51
	s_waitcnt lgkmcnt(2)
	v_pk_add_f32 v[238:239], v[238:239], v[100:101] op_sel:[0,1] op_sel_hi:[1,0]
	ds_read2_b32 v[100:101], v104 offset0:18 offset1:19
	s_waitcnt lgkmcnt(1)
	v_pk_add_f32 v[240:241], v[240:241], v[98:99] op_sel:[0,1] op_sel_hi:[1,0]
	ds_read2_b32 v[98:99], v104 offset0:16 offset1:17
	s_waitcnt lgkmcnt(1)
	v_pk_add_f32 v[138:139], v[138:139], v[100:101] op_sel:[0,1] op_sel_hi:[1,0]
	ds_read2_b32 v[100:101], v104 offset0:42 offset1:43
	v_pk_add_f32 v[136:137], v[136:137], v[96:97] op_sel:[0,1] op_sel_hi:[1,0]
	ds_read2_b32 v[96:97], v104 offset0:48 offset1:49
	s_waitcnt lgkmcnt(1)
	v_pk_add_f32 v[244:245], v[244:245], v[100:101] op_sel:[0,1] op_sel_hi:[1,0]
	ds_read2_b32 v[100:101], v104 offset0:8 offset1:9
	s_waitcnt lgkmcnt(1)
	v_pk_add_f32 v[242:243], v[242:243], v[96:97] op_sel:[0,1] op_sel_hi:[1,0]
	ds_read2_b32 v[96:97], v104 offset0:10 offset1:11
	v_pk_add_f32 v[140:141], v[140:141], v[98:99] op_sel:[0,1] op_sel_hi:[1,0]
	ds_read2_b32 v[98:99], v104 offset0:40 offset1:41
	s_waitcnt lgkmcnt(2)
	v_pk_add_f32 v[144:145], v[144:145], v[100:101] op_sel:[0,1] op_sel_hi:[1,0]
	s_waitcnt lgkmcnt(1)
	v_pk_add_f32 v[142:143], v[142:143], v[96:97] op_sel:[0,1] op_sel_hi:[1,0]
	ds_read2_b32 v[96:97], v104 offset0:34 offset1:35
	s_waitcnt lgkmcnt(1)
	v_pk_add_f32 v[246:247], v[246:247], v[98:99] op_sel:[0,1] op_sel_hi:[1,0]
	ds_read2_b32 v[98:99], v104 offset0:2 offset1:3
	ds_read2_b32 v[102:103], v104 offset0:32 offset1:33
	ds_read2_b32 v[104:105], v104 offset1:1
	s_waitcnt lgkmcnt(3)
	v_pk_add_f32 v[248:249], v[248:249], v[96:97] op_sel:[0,1] op_sel_hi:[1,0]
	s_waitcnt lgkmcnt(2)
	v_pk_add_f32 v[146:147], v[146:147], v[98:99] op_sel:[0,1] op_sel_hi:[1,0]
	s_waitcnt lgkmcnt(1)
	v_pk_add_f32 v[250:251], v[250:251], v[102:103] op_sel:[0,1] op_sel_hi:[1,0]
	s_waitcnt lgkmcnt(0)
	v_pk_add_f32 v[148:149], v[148:149], v[104:105] op_sel:[0,1] op_sel_hi:[1,0]
	s_waitcnt lgkmcnt(0)
	v_mfma_f32_32x32x16_bf16 v[64:79], v[154:157], v[92:95], v[220:235]
	ds_read_b64_tr_b16 v[186:187], v218
	ds_read_b64_tr_b16 v[188:189], v218 offset:512
	ds_read_b64_tr_b16 v[190:191], v218 offset:1024
	ds_read_b64_tr_b16 v[192:193], v218 offset:1536
	ds_read_b64_tr_b16 v[194:195], v218 offset:2048
	ds_read_b64_tr_b16 v[196:197], v218 offset:2560
	ds_read_b64_tr_b16 v[198:199], v218 offset:3072
	ds_read_b64_tr_b16 v[200:201], v218 offset:3584
	ds_read_b64_tr_b16 v[202:203], v218 offset:4096
	ds_read_b64_tr_b16 v[204:205], v218 offset:4608
	ds_read_b64_tr_b16 v[206:207], v218 offset:5120
	v_mfma_f32_32x32x16_bf16 v[48:63], v[158:161], v[92:95], v[220:235]
	ds_read_b64_tr_b16 v[208:209], v218 offset:5632
	ds_read_b64_tr_b16 v[210:211], v218 offset:6144
	ds_read_b64_tr_b16 v[212:213], v218 offset:6656
	ds_read_b64_tr_b16 v[214:215], v218 offset:7168
	ds_read_b64_tr_b16 v[216:217], v218 offset:7680
	v_exp_f32_e32 v236, v236
	v_exp_f32_e32 v134, v134
	v_exp_f32_e32 v237, v237
	v_exp_f32_e32 v135, v135
	v_exp_f32_e32 v238, v238
	v_exp_f32_e32 v136, v136
	v_mfma_f32_32x32x16_bf16 v[64:79], v[162:165], v[88:91], v[64:79]
	v_exp_f32_e32 v239, v239
	v_exp_f32_e32 v137, v137
	v_add_f32_e32 v252, v134, v236
	v_exp_f32_e32 v240, v240
	v_exp_f32_e32 v138, v138
	v_add_f32_e32 v252, 0, v252
	v_add_f32_e32 v253, v135, v237
	v_exp_f32_e32 v241, v241
	v_exp_f32_e32 v139, v139
	v_add_f32_e32 v252, v253, v252
	v_add_f32_e32 v253, v136, v238
	v_mfma_f32_32x32x16_bf16 v[48:63], v[166:169], v[88:91], v[48:63]
	v_exp_f32_e32 v242, v242
	v_exp_f32_e32 v140, v140
	v_add_f32_e32 v252, v253, v252
	v_add_f32_e32 v253, v137, v239
	v_exp_f32_e32 v243, v243
	v_exp_f32_e32 v141, v141
	v_add_f32_e32 v252, v253, v252
	v_add_f32_e32 v253, v138, v240
	v_exp_f32_e32 v244, v244
	v_exp_f32_e32 v142, v142
	v_add_f32_e32 v252, v253, v252
	v_mfma_f32_32x32x16_bf16 v[64:79], v[170:173], v[84:87], v[64:79]
	v_add_f32_e32 v253, v139, v241
	v_exp_f32_e32 v245, v245
	v_exp_f32_e32 v143, v143
	v_add_f32_e32 v252, v253, v252
	v_add_f32_e32 v253, v140, v242
	v_exp_f32_e32 v246, v246
	v_exp_f32_e32 v144, v144
	v_add_f32_e32 v252, v253, v252
	v_add_f32_e32 v253, v141, v243
	v_exp_f32_e32 v247, v247
	v_exp_f32_e32 v145, v145
	v_mfma_f32_32x32x16_bf16 v[48:63], v[174:177], v[84:87], v[48:63]
	v_add_f32_e32 v252, v253, v252
	v_add_f32_e32 v253, v142, v244
	v_exp_f32_e32 v248, v248
	v_exp_f32_e32 v146, v146
	v_add_f32_e32 v252, v253, v252
	v_add_f32_e32 v253, v143, v245
	v_exp_f32_e32 v249, v249
	v_exp_f32_e32 v147, v147
	v_add_f32_e32 v252, v253, v252
	v_add_f32_e32 v253, v144, v246
	v_exp_f32_e32 v250, v250
	v_mfma_f32_32x32x16_bf16 v[64:79], v[178:181], v[80:83], v[64:79]
	v_exp_f32_e32 v148, v148
	v_add_f32_e32 v252, v253, v252
	v_add_f32_e32 v253, v145, v247
	v_exp_f32_e32 v251, v251
	v_exp_f32_e32 v149, v149
	v_add_f32_e32 v252, v253, v252
	v_add_f32_e32 v253, v146, v248
	v_add_f32_e32 v252, v253, v252
	v_add_f32_e32 v253, v147, v249
	v_add_f32_e32 v252, v253, v252
	v_add_f32_e32 v253, v148, v250
	v_mfma_f32_32x32x16_bf16 v[48:63], v[182:185], v[80:83], v[48:63]
	v_add_f32_e32 v252, v253, v252
	v_add_f32_e32 v253, v149, v251
	v_add_f32_e32 v252, v253, v252
	v_add_f32_e32 v131, v131, v252
	v_cvt_pk_bf16_f32 v108, v236, v237
	v_cvt_pk_bf16_f32 v109, v238, v239
	v_cvt_pk_bf16_f32 v110, v240, v241
	v_cvt_pk_bf16_f32 v111, v242, v243
	v_cvt_pk_bf16_f32 v104, v244, v245
	v_cvt_pk_bf16_f32 v105, v246, v247
	v_cvt_pk_bf16_f32 v106, v248, v249
	v_cvt_pk_bf16_f32 v107, v250, v251
	v_cvt_pk_bf16_f32 v100, v134, v135
	v_cvt_pk_bf16_f32 v101, v136, v137
	v_cvt_pk_bf16_f32 v102, v138, v139
	v_cvt_pk_bf16_f32 v103, v140, v141
	v_cvt_pk_bf16_f32 v96, v142, v143
	v_cvt_pk_bf16_f32 v97, v144, v145
	v_cvt_pk_bf16_f32 v98, v146, v147
	v_cvt_pk_bf16_f32 v99, v148, v149
	s_branch .Lmb1_B_tail

; template <int MODE> __device__ __forceinline__ void attn_unit(int b, int h, int qb, int t_lo, const bf16_t* Q, const bf16_t* __restrict__ K, const bf16_t* __restrict__ V, bf16_t* O, ATT_LAS unsigned char* lds, const int wid, const float kn2, const float bmax) {
;     ...
;     if (grp == 0) asm volatile("s_barrier" ::: "memory");
.Lmb1_exitfix:
	s_waitcnt vmcnt(0)
	s_and_b64 vcc, exec, s[6:7]
	s_cbranch_vccnz .LBB0_1075
	s_barrier
	s_branch .LBB0_1075

.LBB0_2383:
.LBB0_2384:
.LBB0_2386:
.Lmb3_A:
	s_barrier
	s_and_b64 vcc, exec, s[6:7]
	s_cbranch_vccz .Lmb3_A_g1top
	s_cmp_eq_u32 s35, 0
	s_cbranch_scc1 .Lmb3_f1A
	s_mov_b32 s42, s35
	s_cmp_ge_u32 s42, s28
	s_cbranch_scc1 .Lmb3_k0A
	s_mov_b32 s42, s43
	s_and_b32 s42, s42, 0x6000
	s_add_i32 s42, s42, s74
	s_mov_b32 s99, m0
	s_mov_b32 m0, s42
	s_nop 0
	global_load_lds_dwordx4 v[114:115], off
	s_mov_b32 m0, s99

.Lmb3_f1A:
	s_add_i32 s42, s35, 1
	s_cmp_ge_u32 s42, s28
	s_cbranch_scc1 .Lmb3_k1A
	s_add_i32 s42, s43, 0x2000
	s_and_b32 s42, s42, 0x6000
	s_add_i32 s42, s42, s74
	s_mov_b32 s99, m0
	s_mov_b32 m0, s42
	s_nop 0
	global_load_lds_dwordx4 v[114:115], off
	s_mov_b32 m0, s99
.Lmb3_k1A:
	v_lshl_add_u64 v[114:115], v[114:115], 0, s[20:21]
	s_cmp_eq_u32 s35, 0
	s_cbranch_scc1 .Lmb3_f2A
	s_add_i32 s42, s35, 3
	s_cmp_ge_u32 s42, s31
	s_cbranch_scc1 .Lmb3_v0A
	s_add_i32 s42, s43, 0x6000
	s_and_b32 s42, s42, 0x6000
	s_add_i32 s42, s42, s75
	s_mov_b32 s99, m0
	s_mov_b32 m0, s42
	s_nop 0
	global_load_lds_dwordx4 v[116:117], off
	s_mov_b32 m0, s99
.Lmb3_v0A:
	v_lshl_add_u64 v[116:117], v[116:117], 0, s[20:21]
.Lmb3_f2A:
	s_add_i32 s42, s35, 4
	s_cmp_ge_u32 s42, s31
	s_cbranch_scc1 .Lmb3_v1A
	s_mov_b32 s42, s43
	s_and_b32 s42, s42, 0x6000
	s_add_i32 s42, s42, s75
	s_mov_b32 s99, m0
	s_mov_b32 m0, s42
	s_nop 0
	global_load_lds_dwordx4 v[116:117], off
	s_mov_b32 m0, s99

; #define ATT_LAS __attribute__((address_space(3)))
; #define ATT_MFMA(a, b, c) __builtin_amdgcn_mfma_f32_32x32x16_bf16((a), (b), (c), 0, 0, 0)
; __device__ __forceinline__ void qkt(f32x16& p0, f32x16& p1, lds_cptr kb, const bf16x8* qr, const f32x16& z) {
; #pragma unroll
;     for (int d0 = 0; d0 < 4; ++d0) {
;         const bf16x8 b0 = *(const ATT_LAS bf16x8*)(kb + d0 * 2048);
;         const bf16x8 b1 = *(const ATT_LAS bf16x8*)(kb + d0 * 2048 + 512);
;         if (d0 == 0) { p0 = ATT_MFMA(b0, qr[0], z); p1 = ATT_MFMA(b1, qr[0], z); }
;         else { p0 = ATT_MFMA(b0, qr[d0], p0); p1 = ATT_MFMA(b1, qr[d0], p1); } }
; }
; __device__ __forceinline__ void pv(f32x16* o, int vb, bf16x8 pa0, bf16x8 pa1, bf16x8 pa2, bf16x8 pa3) {
; #pragma unroll
;     for (int d0 = 0; d0 < 2; ++d0) { s16x4 lo[4], hi[4];
; #pragma unroll
;         for (int ks = 0; ks < 4; ++ks) {
;             asm volatile("ds_read_b64_tr_b16 %0,%1 offset:%c2" : "=&v"(lo[ks]) : "v"(vb), "i"(d0 * 4096 + ks * 1024) : "memory");
;             asm volatile("ds_read_b64_tr_b16 %0,%1 offset:%c2" : "=&v"(hi[ks]) : "v"(vb), "i"(d0 * 4096 + ks * 1024 + 512) : "memory"); }
;         asm volatile("s_waitcnt lgkmcnt(0)" ::: "memory"); __builtin_amdgcn_sched_barrier(0);
;     ...
;         o[d0] = ATT_MFMA(pa0, ATT_PK(0), o[d0]);
;         o[d0] = ATT_MFMA(pa1, ATT_PK(1), o[d0]);
;         o[d0] = ATT_MFMA(pa2, ATT_PK(2), o[d0]);
;         o[d0] = ATT_MFMA(pa3, ATT_PK(3), o[d0]);
;     ...
;     }
; }
.Lmb3_A_g1top:
	s_add_i32 s36, s43, 0x2000
	s_add_i32 s98, s43, 0x4000
	s_and_b32 s42, s98, 0x6000
	v_add_u32_e32 v133, s42, v130
	ds_read_b128 v[154:157], v133
	ds_read_b128 v[158:161], v133 offset:512
	ds_read_b128 v[162:165], v133 offset:2048
	ds_read_b128 v[166:169], v133 offset:2560
	ds_read_b128 v[170:173], v133 offset:4096
	ds_read_b128 v[174:177], v133 offset:4608
	ds_read_b128 v[178:181], v133 offset:6144
	ds_read_b128 v[182:185], v133 offset:6656
	s_and_b32 s42, s36, 0x6000
	v_add_u32_e32 v218, s42, v132
	s_add_i32 s98, s30, 2
	s_cmp_ge_i32 s30, s29
	s_cbranch_scc1 .Lmb3_A_near
	v_mfma_f32_32x32x16_bf16 v[16:31], v[108:111], v[186:189], v[16:31]
	v_exp_f32_e32 v64, v64
	v_exp_f32_e32 v48, v48
	v_mfma_f32_32x32x16_bf16 v[16:31], v[104:107], v[190:193], v[16:31]
	v_exp_f32_e32 v65, v65
	v_exp_f32_e32 v49, v49
	v_add_f32_e32 v252, v64, v48
	v_mfma_f32_32x32x16_bf16 v[16:31], v[100:103], v[194:197], v[16:31]
	v_exp_f32_e32 v66, v66
	v_exp_f32_e32 v50, v50
	v_add_f32_e32 v253, v65, v49
	v_add_f32_e32 v252, v252, v253
	v_mfma_f32_32x32x16_bf16 v[16:31], v[96:99], v[198:201], v[16:31]
	v_exp_f32_e32 v67, v67
	v_exp_f32_e32 v51, v51
	v_add_f32_e32 v253, v66, v50
	v_add_f32_e32 v252, v252, v253
	v_mfma_f32_32x32x16_bf16 v[32:47], v[108:111], v[202:205], v[32:47]
	v_exp_f32_e32 v68, v68
	v_exp_f32_e32 v52, v52
	v_add_f32_e32 v253, v67, v51
	v_add_f32_e32 v252, v252, v253
	ds_read_b64_tr_b16 v[186:187], v218
	ds_read_b64_tr_b16 v[188:189], v218 offset:512
	v_mfma_f32_32x32x16_bf16 v[32:47], v[104:107], v[206:209], v[32:47]
	v_exp_f32_e32 v69, v69
	v_exp_f32_e32 v53, v53
	v_add_f32_e32 v253, v68, v52
	v_add_f32_e32 v252, v252, v253
	ds_read_b64_tr_b16 v[190:191], v218 offset:1024
	ds_read_b64_tr_b16 v[192:193], v218 offset:1536
	v_mfma_f32_32x32x16_bf16 v[32:47], v[100:103], v[210:213], v[32:47]
	v_exp_f32_e32 v70, v70
	v_exp_f32_e32 v54, v54
	v_add_f32_e32 v253, v69, v53
	v_add_f32_e32 v252, v252, v253
	ds_read_b64_tr_b16 v[194:195], v218 offset:2048
	ds_read_b64_tr_b16 v[196:197], v218 offset:2560
	v_mfma_f32_32x32x16_bf16 v[32:47], v[96:99], v[214:217], v[32:47]
	v_exp_f32_e32 v71, v71
	v_exp_f32_e32 v55, v55
	v_add_f32_e32 v253, v70, v54
	v_add_f32_e32 v252, v252, v253
	ds_read_b64_tr_b16 v[198:199], v218 offset:3072
	ds_read_b64_tr_b16 v[200:201], v218 offset:3584
	s_and_b64 vcc, exec, s[6:7]
	s_cbranch_vccnz .Lmb3_A_g0mid
	s_cmp_eq_u32 s35, 0
	s_cbranch_scc1 .Lmb3_f1Am
	s_mov_b32 s42, s35
	s_cmp_ge_u32 s42, s28
	s_cbranch_scc1 .Lmb3_k0Am
	s_mov_b32 s42, s43
	s_and_b32 s42, s42, 0x6000
	s_add_i32 s42, s42, s74
	s_mov_b32 s99, m0
	s_mov_b32 m0, s42
	s_nop 0
	global_load_lds_dwordx4 v[114:115], off
	s_mov_b32 m0, s99

.Lmb3_A_nocin:
	v_subrev_u32_e32 v112, 64, v112
	s_add_i32 s30, s30, 1
	s_waitcnt lgkmcnt(0)

; #define ATT_LAS __attribute__((address_space(3)))
; #define ATT_MFMA(a, b, c) __builtin_amdgcn_mfma_f32_32x32x16_bf16((a), (b), (c), 0, 0, 0)
; __device__ __forceinline__ void qkt(f32x16& p0, f32x16& p1, lds_cptr kb, const bf16x8* qr, const f32x16& z) {
; #pragma unroll
;     for (int d0 = 0; d0 < 4; ++d0) {
;         const bf16x8 b0 = *(const ATT_LAS bf16x8*)(kb + d0 * 2048);
;         const bf16x8 b1 = *(const ATT_LAS bf16x8*)(kb + d0 * 2048 + 512);
;         if (d0 == 0) { p0 = ATT_MFMA(b0, qr[0], z); p1 = ATT_MFMA(b1, qr[0], z); }
;         else { p0 = ATT_MFMA(b0, qr[d0], p0); p1 = ATT_MFMA(b1, qr[d0], p1); } }
; }
; __device__ __forceinline__ void pv(f32x16* o, int vb, bf16x8 pa0, bf16x8 pa1, bf16x8 pa2, bf16x8 pa3) {
; #pragma unroll
;     for (int d0 = 0; d0 < 2; ++d0) { s16x4 lo[4], hi[4];
; #pragma unroll
;         for (int ks = 0; ks < 4; ++ks) {
;             asm volatile("ds_read_b64_tr_b16 %0,%1 offset:%c2" : "=&v"(lo[ks]) : "v"(vb), "i"(d0 * 4096 + ks * 1024) : "memory");
;             asm volatile("ds_read_b64_tr_b16 %0,%1 offset:%c2" : "=&v"(hi[ks]) : "v"(vb), "i"(d0 * 4096 + ks * 1024 + 512) : "memory"); }
;         asm volatile("s_waitcnt lgkmcnt(0)" ::: "memory"); __builtin_amdgcn_sched_barrier(0);
;     ...
;         o[d0] = ATT_MFMA(pa0, ATT_PK(0), o[d0]);
;         o[d0] = ATT_MFMA(pa1, ATT_PK(1), o[d0]);
;         o[d0] = ATT_MFMA(pa2, ATT_PK(2), o[d0]);
;         o[d0] = ATT_MFMA(pa3, ATT_PK(3), o[d0]);
;     ...
;     }
; }
.Lmb3_B_g1top:
	s_add_i32 s36, s43, 0x2000
	s_add_i32 s98, s43, 0x4000
	s_and_b32 s42, s98, 0x6000
	v_add_u32_e32 v133, s42, v130
	ds_read_b128 v[154:157], v133
	ds_read_b128 v[158:161], v133 offset:512
	ds_read_b128 v[162:165], v133 offset:2048
	ds_read_b128 v[166:169], v133 offset:2560
	ds_read_b128 v[170:173], v133 offset:4096
	ds_read_b128 v[174:177], v133 offset:4608
	ds_read_b128 v[178:181], v133 offset:6144
	ds_read_b128 v[182:185], v133 offset:6656
	s_and_b32 s42, s36, 0x6000
	v_add_u32_e32 v218, s42, v132
	s_add_i32 s98, s30, 2
	s_cmp_ge_i32 s30, s29
	s_cbranch_scc1 .Lmb3_B_near
	v_mfma_f32_32x32x16_bf16 v[16:31], v[108:111], v[186:189], v[16:31]
	v_exp_f32_e32 v236, v236
	v_exp_f32_e32 v134, v134
	v_mfma_f32_32x32x16_bf16 v[16:31], v[104:107], v[190:193], v[16:31]
	v_exp_f32_e32 v237, v237
	v_exp_f32_e32 v135, v135
	v_add_f32_e32 v252, v236, v134
	v_mfma_f32_32x32x16_bf16 v[16:31], v[100:103], v[194:197], v[16:31]
	v_exp_f32_e32 v238, v238
	v_exp_f32_e32 v136, v136
	v_add_f32_e32 v253, v237, v135
	v_add_f32_e32 v252, v252, v253
	v_mfma_f32_32x32x16_bf16 v[16:31], v[96:99], v[198:201], v[16:31]
	v_exp_f32_e32 v239, v239
	v_exp_f32_e32 v137, v137
	v_add_f32_e32 v253, v238, v136
	v_add_f32_e32 v252, v252, v253
	v_mfma_f32_32x32x16_bf16 v[32:47], v[108:111], v[202:205], v[32:47]
	v_exp_f32_e32 v240, v240
	v_exp_f32_e32 v138, v138
	v_add_f32_e32 v253, v239, v137
	v_add_f32_e32 v252, v252, v253
	ds_read_b64_tr_b16 v[186:187], v218
	ds_read_b64_tr_b16 v[188:189], v218 offset:512
	v_mfma_f32_32x32x16_bf16 v[32:47], v[104:107], v[206:209], v[32:47]
	v_exp_f32_e32 v241, v241
	v_exp_f32_e32 v139, v139
	v_add_f32_e32 v253, v240, v138
	v_add_f32_e32 v252, v252, v253
	ds_read_b64_tr_b16 v[190:191], v218 offset:1024
	ds_read_b64_tr_b16 v[192:193], v218 offset:1536
	v_mfma_f32_32x32x16_bf16 v[32:47], v[100:103], v[210:213], v[32:47]
	v_exp_f32_e32 v242, v242
	v_exp_f32_e32 v140, v140
	v_add_f32_e32 v253, v241, v139
	v_add_f32_e32 v252, v252, v253
	ds_read_b64_tr_b16 v[194:195], v218 offset:2048
	ds_read_b64_tr_b16 v[196:197], v218 offset:2560
	v_mfma_f32_32x32x16_bf16 v[32:47], v[96:99], v[214:217], v[32:47]
	v_exp_f32_e32 v243, v243
	v_exp_f32_e32 v141, v141
	v_add_f32_e32 v253, v242, v140
	v_add_f32_e32 v252, v252, v253
	ds_read_b64_tr_b16 v[198:199], v218 offset:3072
	ds_read_b64_tr_b16 v[200:201], v218 offset:3584
	s_and_b64 vcc, exec, s[6:7]
	s_cbranch_vccnz .Lmb3_B_g0mid
.Lmb3_B_g0mid:
	s_waitcnt lgkmcnt(8)
	v_mfma_f32_32x32x16_bf16 v[64:79], v[154:157], v[92:95], v[220:235]
	v_exp_f32_e32 v244, v244
	v_exp_f32_e32 v142, v142
	v_add_f32_e32 v253, v243, v141
	v_add_f32_e32 v252, v252, v253
	v_cvt_pk_bf16_f32 v108, v236, v237
	v_cvt_pk_bf16_f32 v100, v134, v135
	ds_read_b64_tr_b16 v[202:203], v218 offset:4096
	ds_read_b64_tr_b16 v[204:205], v218 offset:4608
	v_mfma_f32_32x32x16_bf16 v[48:63], v[158:161], v[92:95], v[220:235]
	v_exp_f32_e32 v245, v245
	v_exp_f32_e32 v143, v143
	v_add_f32_e32 v253, v244, v142
	v_add_f32_e32 v252, v252, v253
	v_cvt_pk_bf16_f32 v109, v238, v239
	v_cvt_pk_bf16_f32 v101, v136, v137
	ds_read_b64_tr_b16 v[206:207], v218 offset:5120
	ds_read_b64_tr_b16 v[208:209], v218 offset:5632
	v_mfma_f32_32x32x16_bf16 v[64:79], v[162:165], v[88:91], v[64:79]
	v_exp_f32_e32 v246, v246
	v_exp_f32_e32 v144, v144
	v_add_f32_e32 v253, v245, v143
	v_add_f32_e32 v252, v252, v253
	v_cvt_pk_bf16_f32 v110, v240, v241
	v_cvt_pk_bf16_f32 v102, v138, v139
	ds_read_b64_tr_b16 v[210:211], v218 offset:6144
	ds_read_b64_tr_b16 v[212:213], v218 offset:6656
	v_mfma_f32_32x32x16_bf16 v[48:63], v[166:169], v[88:91], v[48:63]
	v_exp_f32_e32 v247, v247
	v_exp_f32_e32 v145, v145
	v_add_f32_e32 v253, v246, v144
	v_add_f32_e32 v252, v252, v253
	v_cvt_pk_bf16_f32 v111, v242, v243
	v_cvt_pk_bf16_f32 v103, v140, v141
	ds_read_b64_tr_b16 v[214:215], v218 offset:7168
	ds_read_b64_tr_b16 v[216:217], v218 offset:7680
	v_mfma_f32_32x32x16_bf16 v[64:79], v[170:173], v[84:87], v[64:79]
	v_exp_f32_e32 v248, v248
	v_exp_f32_e32 v146, v146
	v_add_f32_e32 v253, v247, v145
	v_add_f32_e32 v252, v252, v253
	v_cvt_pk_bf16_f32 v104, v244, v245
	v_cvt_pk_bf16_f32 v96, v142, v143
	v_mfma_f32_32x32x16_bf16 v[48:63], v[174:177], v[84:87], v[48:63]
	v_exp_f32_e32 v249, v249
	v_exp_f32_e32 v147, v147
	v_add_f32_e32 v253, v248, v146
	v_add_f32_e32 v252, v252, v253
	v_cvt_pk_bf16_f32 v105, v246, v247
	v_cvt_pk_bf16_f32 v97, v144, v145
	v_mfma_f32_32x32x16_bf16 v[64:79], v[178:181], v[80:83], v[64:79]
	v_exp_f32_e32 v250, v250
	v_exp_f32_e32 v148, v148
	v_add_f32_e32 v253, v249, v147
	v_add_f32_e32 v252, v252, v253
	v_cvt_pk_bf16_f32 v106, v248, v249
	v_cvt_pk_bf16_f32 v98, v146, v147
	v_mfma_f32_32x32x16_bf16 v[48:63], v[182:185], v[80:83], v[48:63]
	v_exp_f32_e32 v251, v251
	v_exp_f32_e32 v149, v149
	v_add_f32_e32 v253, v250, v148
	v_add_f32_e32 v252, v252, v253
	v_add_f32_e32 v253, v251, v149
	v_add_f32_e32 v252, v252, v253
	v_cvt_pk_bf16_f32 v107, v250, v251
	v_cvt_pk_bf16_f32 v99, v148, v149
	v_add_f32_e32 v131, v131, v252

.Lmb3_B_nocin:
	v_subrev_u32_e32 v112, 64, v112
	s_add_i32 s30, s30, 1
	s_waitcnt vmcnt(0) lgkmcnt(0)

.Lmb3_A_near:
	s_and_b64 vcc, exec, s[6:7]
	s_cbranch_vccnz .Lmb3_A_g0near
	s_cmp_eq_u32 s35, 0
	s_cbranch_scc1 .Lmb3_f1An
	s_mov_b32 s42, s35
	s_cmp_ge_u32 s42, s28
	s_cbranch_scc1 .Lmb3_k0An
	s_mov_b32 s42, s43
	s_and_b32 s42, s42, 0x6000
	s_add_i32 s42, s42, s74
	s_mov_b32 s99, m0
	s_mov_b32 m0, s42
	s_nop 0
	global_load_lds_dwordx4 v[114:115], off
	s_mov_b32 m0, s99

; #define ATT_MFMA(a, b, c) __builtin_amdgcn_mfma_f32_32x32x16_bf16((a), (b), (c), 0, 0, 0)
; __device__ __forceinline__ void pv(f32x16* o, int vb, bf16x8 pa0, bf16x8 pa1, bf16x8 pa2, bf16x8 pa3) {
; #pragma unroll
;     for (int d0 = 0; d0 < 2; ++d0) { s16x4 lo[4], hi[4];
; #pragma unroll
;         for (int ks = 0; ks < 4; ++ks) {
;             asm volatile("ds_read_b64_tr_b16 %0,%1 offset:%c2" : "=&v"(lo[ks]) : "v"(vb), "i"(d0 * 4096 + ks * 1024) : "memory");
;             asm volatile("ds_read_b64_tr_b16 %0,%1 offset:%c2" : "=&v"(hi[ks]) : "v"(vb), "i"(d0 * 4096 + ks * 1024 + 512) : "memory"); }
;         asm volatile("s_waitcnt lgkmcnt(0)" ::: "memory"); __builtin_amdgcn_sched_barrier(0);
;     ...
;         o[d0] = ATT_MFMA(pa0, ATT_PK(0), o[d0]);
;         o[d0] = ATT_MFMA(pa1, ATT_PK(1), o[d0]);
;         o[d0] = ATT_MFMA(pa2, ATT_PK(2), o[d0]);
;         o[d0] = ATT_MFMA(pa3, ATT_PK(3), o[d0]);
;     ...
;     }
; }
.Lmb3_B_near:
	s_and_b64 vcc, exec, s[6:7]
	s_cbranch_vccnz .Lmb3_B_g0near
.Lmb3_B_g0near:
	s_waitcnt lgkmcnt(8)
	v_mfma_f32_32x32x16_bf16 v[16:31], v[108:111], v[186:189], v[16:31]
	v_mfma_f32_32x32x16_bf16 v[16:31], v[104:107], v[190:193], v[16:31]
	v_mfma_f32_32x32x16_bf16 v[16:31], v[100:103], v[194:197], v[16:31]
	v_mfma_f32_32x32x16_bf16 v[16:31], v[96:99], v[198:201], v[16:31]
	v_mfma_f32_32x32x16_bf16 v[32:47], v[108:111], v[202:205], v[32:47]
	v_mfma_f32_32x32x16_bf16 v[32:47], v[104:107], v[206:209], v[32:47]
	v_mfma_f32_32x32x16_bf16 v[32:47], v[100:103], v[210:213], v[32:47]
	v_mfma_f32_32x32x16_bf16 v[32:47], v[96:99], v[214:217], v[32:47]
	s_lshr_b32 s42, s30, 2
	s_cmp_eq_u32 s42, s93
	s_cselect_b64 s[10:11], -1, 0
	s_lshl_b32 s42, 1, s42
	v_and_b32_e32 v96, s42, v129
	v_cmp_ne_u32_e32 vcc, 0, v96
	s_or_b64 vcc, s[10:11], vcc
	s_nop 0
	v_cndmask_b32_e32 v96, v127, v112, vcc
	v_lshl_add_u32 v96, v96, 2, 0
	v_add_u32_e32 v104, 0x1d000, v96
	ds_read2_b32 v[96:97], v104 offset0:58 offset1:59
	ds_read2_b32 v[98:99], v104 offset0:26 offset1:27
	ds_read2_b32 v[100:101], v104 offset0:56 offset1:57
	s_waitcnt lgkmcnt(2)
	v_pk_add_f32 v[236:237], v[236:237], v[96:97] op_sel:[0,1] op_sel_hi:[1,0]
	ds_read2_b32 v[96:97], v104 offset0:24 offset1:25
	s_waitcnt lgkmcnt(2)
	v_pk_add_f32 v[134:135], v[134:135], v[98:99] op_sel:[0,1] op_sel_hi:[1,0]
	ds_read2_b32 v[98:99], v104 offset0:50 offset1:51
	s_waitcnt lgkmcnt(2)
	v_pk_add_f32 v[238:239], v[238:239], v[100:101] op_sel:[0,1] op_sel_hi:[1,0]
	ds_read2_b32 v[100:101], v104 offset0:18 offset1:19
	s_waitcnt lgkmcnt(1)
	v_pk_add_f32 v[240:241], v[240:241], v[98:99] op_sel:[0,1] op_sel_hi:[1,0]
	ds_read2_b32 v[98:99], v104 offset0:16 offset1:17
	s_waitcnt lgkmcnt(1)
	v_pk_add_f32 v[138:139], v[138:139], v[100:101] op_sel:[0,1] op_sel_hi:[1,0]
	ds_read2_b32 v[100:101], v104 offset0:42 offset1:43
	v_pk_add_f32 v[136:137], v[136:137], v[96:97] op_sel:[0,1] op_sel_hi:[1,0]
	ds_read2_b32 v[96:97], v104 offset0:48 offset1:49
	s_waitcnt lgkmcnt(1)
	v_pk_add_f32 v[244:245], v[244:245], v[100:101] op_sel:[0,1] op_sel_hi:[1,0]
	ds_read2_b32 v[100:101], v104 offset0:8 offset1:9
	s_waitcnt lgkmcnt(1)
	v_pk_add_f32 v[242:243], v[242:243], v[96:97] op_sel:[0,1] op_sel_hi:[1,0]
	ds_read2_b32 v[96:97], v104 offset0:10 offset1:11
	v_pk_add_f32 v[140:141], v[140:141], v[98:99] op_sel:[0,1] op_sel_hi:[1,0]
	ds_read2_b32 v[98:99], v104 offset0:40 offset1:41
	s_waitcnt lgkmcnt(2)
	v_pk_add_f32 v[144:145], v[144:145], v[100:101] op_sel:[0,1] op_sel_hi:[1,0]
	s_waitcnt lgkmcnt(1)
	v_pk_add_f32 v[142:143], v[142:143], v[96:97] op_sel:[0,1] op_sel_hi:[1,0]
	ds_read2_b32 v[96:97], v104 offset0:34 offset1:35
	s_waitcnt lgkmcnt(1)
	v_pk_add_f32 v[246:247], v[246:247], v[98:99] op_sel:[0,1] op_sel_hi:[1,0]
	ds_read2_b32 v[98:99], v104 offset0:2 offset1:3
	ds_read2_b32 v[102:103], v104 offset0:32 offset1:33
	ds_read2_b32 v[104:105], v104 offset1:1
	s_waitcnt lgkmcnt(3)
	v_pk_add_f32 v[248:249], v[248:249], v[96:97] op_sel:[0,1] op_sel_hi:[1,0]
	s_waitcnt lgkmcnt(2)
	v_pk_add_f32 v[146:147], v[146:147], v[98:99] op_sel:[0,1] op_sel_hi:[1,0]
	s_waitcnt lgkmcnt(1)
	v_pk_add_f32 v[250:251], v[250:251], v[102:103] op_sel:[0,1] op_sel_hi:[1,0]
	s_waitcnt lgkmcnt(0)
	v_pk_add_f32 v[148:149], v[148:149], v[104:105] op_sel:[0,1] op_sel_hi:[1,0]
	s_waitcnt lgkmcnt(0)
; #define ATT_LAS __attribute__((address_space(3)))
; #define ATT_MFMA(a, b, c) __builtin_amdgcn_mfma_f32_32x32x16_bf16((a), (b), (c), 0, 0, 0)
; __device__ __forceinline__ void qkt(f32x16& p0, f32x16& p1, lds_cptr kb, const bf16x8* qr, const f32x16& z) {
; #pragma unroll
;     for (int d0 = 0; d0 < 4; ++d0) {
;         const bf16x8 b0 = *(const ATT_LAS bf16x8*)(kb + d0 * 2048);
;         const bf16x8 b1 = *(const ATT_LAS bf16x8*)(kb + d0 * 2048 + 512);
;         if (d0 == 0) { p0 = ATT_MFMA(b0, qr[0], z); p1 = ATT_MFMA(b1, qr[0], z); }
;         else { p0 = ATT_MFMA(b0, qr[d0], p0); p1 = ATT_MFMA(b1, qr[d0], p1); } }
; }
	v_mfma_f32_32x32x16_bf16 v[64:79], v[154:157], v[92:95], v[220:235]
	ds_read_b64_tr_b16 v[186:187], v218
	ds_read_b64_tr_b16 v[188:189], v218 offset:512
	ds_read_b64_tr_b16 v[190:191], v218 offset:1024
	ds_read_b64_tr_b16 v[192:193], v218 offset:1536
	ds_read_b64_tr_b16 v[194:195], v218 offset:2048
	ds_read_b64_tr_b16 v[196:197], v218 offset:2560
	ds_read_b64_tr_b16 v[198:199], v218 offset:3072
	ds_read_b64_tr_b16 v[200:201], v218 offset:3584
	ds_read_b64_tr_b16 v[202:203], v218 offset:4096
	ds_read_b64_tr_b16 v[204:205], v218 offset:4608
	ds_read_b64_tr_b16 v[206:207], v218 offset:5120
	v_mfma_f32_32x32x16_bf16 v[48:63], v[158:161], v[92:95], v[220:235]
	ds_read_b64_tr_b16 v[208:209], v218 offset:5632
	ds_read_b64_tr_b16 v[210:211], v218 offset:6144
	ds_read_b64_tr_b16 v[212:213], v218 offset:6656
	ds_read_b64_tr_b16 v[214:215], v218 offset:7168
	ds_read_b64_tr_b16 v[216:217], v218 offset:7680
	v_exp_f32_e32 v236, v236
	v_exp_f32_e32 v134, v134
	v_exp_f32_e32 v237, v237
	v_exp_f32_e32 v135, v135
	v_exp_f32_e32 v238, v238
	v_exp_f32_e32 v136, v136
	v_mfma_f32_32x32x16_bf16 v[64:79], v[162:165], v[88:91], v[64:79]
	v_exp_f32_e32 v239, v239
	v_exp_f32_e32 v137, v137
	v_add_f32_e32 v252, v134, v236
	v_exp_f32_e32 v240, v240
	v_exp_f32_e32 v138, v138
	v_add_f32_e32 v252, 0, v252
	v_add_f32_e32 v253, v135, v237
	v_exp_f32_e32 v241, v241
	v_exp_f32_e32 v139, v139
	v_add_f32_e32 v252, v253, v252
	v_add_f32_e32 v253, v136, v238
	v_mfma_f32_32x32x16_bf16 v[48:63], v[166:169], v[88:91], v[48:63]
	v_exp_f32_e32 v242, v242
	v_exp_f32_e32 v140, v140
	v_add_f32_e32 v252, v253, v252
	v_add_f32_e32 v253, v137, v239
	v_exp_f32_e32 v243, v243
	v_exp_f32_e32 v141, v141
	v_add_f32_e32 v252, v253, v252
	v_add_f32_e32 v253, v138, v240
	v_exp_f32_e32 v244, v244
	v_exp_f32_e32 v142, v142
	v_add_f32_e32 v252, v253, v252
	v_mfma_f32_32x32x16_bf16 v[64:79], v[170:173], v[84:87], v[64:79]
	v_add_f32_e32 v253, v139, v241
	v_exp_f32_e32 v245, v245
	v_exp_f32_e32 v143, v143
	v_add_f32_e32 v252, v253, v252
	v_add_f32_e32 v253, v140, v242
	v_exp_f32_e32 v246, v246
	v_exp_f32_e32 v144, v144
	v_add_f32_e32 v252, v253, v252
	v_add_f32_e32 v253, v141, v243
	v_exp_f32_e32 v247, v247
	v_exp_f32_e32 v145, v145
	v_mfma_f32_32x32x16_bf16 v[48:63], v[174:177], v[84:87], v[48:63]
	v_add_f32_e32 v252, v253, v252
	v_add_f32_e32 v253, v142, v244
	v_exp_f32_e32 v248, v248
	v_exp_f32_e32 v146, v146
	v_add_f32_e32 v252, v253, v252
	v_add_f32_e32 v253, v143, v245
	v_exp_f32_e32 v249, v249
	v_exp_f32_e32 v147, v147
	v_add_f32_e32 v252, v253, v252
	v_add_f32_e32 v253, v144, v246
	v_exp_f32_e32 v250, v250
	v_mfma_f32_32x32x16_bf16 v[64:79], v[178:181], v[80:83], v[64:79]
	v_exp_f32_e32 v148, v148
	v_add_f32_e32 v252, v253, v252
	v_add_f32_e32 v253, v145, v247
	v_exp_f32_e32 v251, v251
	v_exp_f32_e32 v149, v149
	v_add_f32_e32 v252, v253, v252
	v_add_f32_e32 v253, v146, v248
	v_add_f32_e32 v252, v253, v252
	v_add_f32_e32 v253, v147, v249
	v_add_f32_e32 v252, v253, v252
	v_add_f32_e32 v253, v148, v250
	v_mfma_f32_32x32x16_bf16 v[48:63], v[182:185], v[80:83], v[48:63]
	v_add_f32_e32 v252, v253, v252
	v_add_f32_e32 v253, v149, v251
	v_add_f32_e32 v252, v253, v252
	v_add_f32_e32 v131, v131, v252
	v_cvt_pk_bf16_f32 v108, v236, v237
	v_cvt_pk_bf16_f32 v109, v238, v239
	v_cvt_pk_bf16_f32 v110, v240, v241
	v_cvt_pk_bf16_f32 v111, v242, v243
	v_cvt_pk_bf16_f32 v104, v244, v245
	v_cvt_pk_bf16_f32 v105, v246, v247
	v_cvt_pk_bf16_f32 v106, v248, v249
	v_cvt_pk_bf16_f32 v107, v250, v251
	v_cvt_pk_bf16_f32 v100, v134, v135
	v_cvt_pk_bf16_f32 v101, v136, v137
	v_cvt_pk_bf16_f32 v102, v138, v139
	v_cvt_pk_bf16_f32 v103, v140, v141
	v_cvt_pk_bf16_f32 v96, v142, v143
	v_cvt_pk_bf16_f32 v97, v144, v145
	v_cvt_pk_bf16_f32 v98, v146, v147
	v_cvt_pk_bf16_f32 v99, v148, v149
	s_branch .Lmb3_B_tail
